# phase 3 queue: per-XCD item queues with stealing, chunk-major order inside an XCD (four (b,h) streams per XCD, up to six chunks of a (b,h) together)
# speedup vs baseline: 1.0051x; 1.0051x over previous
.Lq3_m1:
	s_cmpk_lt_u32 s10, 0x88
	s_cbranch_scc0 .Lq3_m2
	s_add_i32 s10, s10, -8
	s_lshr_b32 s11, s10, 2
	s_lshl_b32 s11, s11, 5
	s_and_b32 s10, s10, 3
	s_add_i32 s10, s10, s11
	s_lshl_b32 s11, s99, 2
	s_add_i32 s10, s10, s11
	s_add_i32 s10, s10, 64
	s_branch .Lq3_done
